# speedup vs baseline: 1.0035x; 1.0035x over previous
; __device__ __forceinline__ int tid_fresh() { int t = (int)threadIdx.x; asm volatile("" : "+v"(t)); return t; }
; __device__ __forceinline__ unsigned cvt_pk_bf16(float lo, float hi) { unsigned r; asm volatile("v_cvt_pk_bf16_f32 %0, %1, %2" : "=v"(r) : "v"(lo), "v"(hi)); return r; }
; __device__ __forceinline__ float wave_sum(float v) {
; #pragma unroll
;     for (int o = 32; o > 0; o >>= 1) v += __shfl_xor(v, o);
;     return v;
; }
; __device__ __forceinline__ void norm_phase(const float* src_l, const float* src_c, int nrows, const float* modl, int shoff, int scoff, bf16_t* xl) {
;     const int lane = tid_fresh() & 63, gw = blockIdx.x * 8 + (tid_fresh() >> 6), NGW = gridDim.x * 8;
;     for (int r = gw; r < nrows; r += NGW) {
;         const bool lat = r < MLAT; const int cond = lat ? (r >> 13) : 8;
;         const float* xr = lat ? src_l + (size_t)r * DM : src_c + (size_t)(r - MLAT) * DM;
;         const float* mp = modl + cond * 6144;
;         f32x4 v[4]; float s = 0.f;
; #pragma unroll
;         for (int j = 0; j < 4; ++j) { v[j] = *(const f32x4*)(xr + 4 * lane + 256 * j); s += v[j][0] * v[j][0] + v[j][1] * v[j][1] + v[j][2] * v[j][2] + v[j][3] * v[j][3]; }
;         const float rstd = rsqrtf(wave_sum(s) * (1.0f / DM) + EPS);
; #pragma unroll
;         for (int j = 0; j < 4; ++j) { const int col = 4 * lane + 256 * j; const f32x4 sc = *(const f32x4*)(mp + scoff + col), sh = *(const f32x4*)(mp + shoff + col);
;             const f32x4 o = v[j] * rstd * (sc + 1.0f) + sh; u32x2 w; w.x = cvt_pk_bf16(o[0], o[1]); w.y = cvt_pk_bf16(o[2], o[3]);
;             *(u32x2*)(xl + (size_t)r * DM + col) = w; }
;     }
; }
.LBB0_56:
	s_or_b64 exec, exec, s[12:13]
	v_lshl_add_u64 v[18:19], v[18:19], 0, v[8:9]
	global_load_dwordx4 v[28:31], v[18:19], off nt
	global_load_dwordx4 v[32:35], v[18:19], off offset:1024 nt
	global_load_dwordx4 v[36:39], v[18:19], off offset:2048 nt
	global_load_dwordx4 v[40:43], v[18:19], off offset:3072 nt
	v_min_i32_e32 v2, 0x10000, v0
	v_ashrrev_i32_e32 v2, 13, v2
	v_mul_i32_i24_e32 v18, 0x1800, v2
	v_ashrrev_i32_e32 v19, 31, v18
	v_lshl_add_u64 v[18:19], v[18:19], 2, s[54:55]
	v_lshl_add_u64 v[52:53], v[18:19], 0, s[10:11]
	v_lshl_add_u64 v[44:45], v[52:53], 0, v[8:9]
	global_load_dwordx4 v[44:47], v[44:45], off
	v_lshl_add_u64 v[54:55], v[18:19], 0, v[8:9]
	global_load_dwordx4 v[48:51], v[54:55], off
	v_lshl_add_u64 v[70:71], v[52:53], 0, v[10:11]
	global_load_dwordx4 v[72:75], v[70:71], off
	global_load_dwordx4 v[76:79], v[54:55], off offset:1024
	v_lshl_add_u64 v[70:71], v[52:53], 0, v[12:13]
	global_load_dwordx4 v[80:83], v[70:71], off
	global_load_dwordx4 v[84:87], v[54:55], off offset:2048
	v_lshl_add_u64 v[70:71], v[52:53], 0, v[14:15]
	global_load_dwordx4 v[88:91], v[70:71], off
	global_load_dwordx4 v[92:95], v[54:55], off offset:3072
	v_lshlrev_b64 v[16:17], 11, v[16:17]
	v_lshl_add_u64 v[0:1], v[0:1], 0, s[78:79]
	v_lshl_add_u64 v[6:7], v[6:7], 0, s[6:7]
	s_waitcnt vmcnt(11)
	v_mov_b32_e32 v56, v29
	s_waitcnt vmcnt(10)
	v_mov_b32_e32 v57, v33
	v_mov_b32_e32 v18, v28
	v_mov_b32_e32 v19, v32
	s_waitcnt vmcnt(9)
	v_mov_b32_e32 v64, v37
	s_waitcnt vmcnt(8)
	v_mov_b32_e32 v65, v41
	v_pk_mul_f32 v[56:57], v[56:57], v[56:57]
	v_mov_b32_e32 v58, v30
	v_mov_b32_e32 v59, v34
	v_mov_b32_e32 v62, v36
	v_mov_b32_e32 v63, v40
	v_pk_mul_f32 v[64:65], v[64:65], v[64:65]
	v_pk_fma_f32 v[18:19], v[18:19], v[18:19], v[56:57]
	v_mov_b32_e32 v60, v31
	v_mov_b32_e32 v61, v35
	v_mov_b32_e32 v66, v38
	v_mov_b32_e32 v67, v42
	v_pk_fma_f32 v[56:57], v[62:63], v[62:63], v[64:65]
	v_pk_fma_f32 v[18:19], v[58:59], v[58:59], v[18:19]
	v_mov_b32_e32 v68, v39
	v_mov_b32_e32 v69, v43
	v_pk_fma_f32 v[56:57], v[66:67], v[66:67], v[56:57]
	v_pk_fma_f32 v[18:19], v[60:61], v[60:61], v[18:19]
	v_pk_fma_f32 v[56:57], v[68:69], v[68:69], v[56:57]
	v_add_f32_e32 v2, v18, v19
	v_add_f32_e32 v2, v2, v56
	v_add_f32_e32 v2, v2, v57
	v_lshl_add_u64 v[56:57], v[4:5], 0, v[16:17]
	s_waitcnt vmcnt(7)
	v_pk_add_f32 v[44:45], v[44:45], 1.0 op_sel_hi:[1,0]
	s_waitcnt lgkmcnt(0)
	s_nop 1
	v_add_f32_dpp v2, v2, v2 quad_perm:[1,0,3,2] row_mask:0xf bank_mask:0xf
	s_waitcnt lgkmcnt(0)
	s_nop 1
	v_add_f32_dpp v2, v2, v2 quad_perm:[2,3,0,1] row_mask:0xf bank_mask:0xf
	s_waitcnt lgkmcnt(0)
	s_nop 1
	v_add_f32_dpp v2, v2, v2 row_half_mirror row_mask:0xf bank_mask:0xf
	s_waitcnt lgkmcnt(0)
	s_nop 1
	v_add_f32_dpp v2, v2, v2 row_mirror row_mask:0xf bank_mask:0xf
	s_waitcnt lgkmcnt(0)
	s_nop 1
	v_add_f32_dpp v2, v2, v2 row_bcast:15 row_mask:0xa bank_mask:0xf
	s_waitcnt lgkmcnt(0)
	s_nop 1
	v_add_f32_dpp v2, v2, v2 row_bcast:31 row_mask:0xc bank_mask:0xf
	s_nop 0
	v_readlane_b32 s100, v2, 63
	s_nop 1
	v_mov_b32_e32 v2, s100
	v_fmamk_f32 v2, v2, 0x3a800000, v26
	v_mul_f32_e32 v16, 0x4b800000, v2
	v_cmp_gt_f32_e32 vcc, s15, v2
	v_pk_add_f32 v[18:19], v[46:47], 1.0 op_sel_hi:[1,0]
	s_nop 0
	v_cndmask_b32_e32 v2, v2, v16, vcc
	v_rsq_f32_e32 v2, v2
	v_lshl_add_u64 v[16:17], v[52:53], 0, v[10:11]
	v_mul_f32_e32 v27, 0x45800000, v2
	v_cndmask_b32_e32 v2, v2, v27, vcc
	v_pk_mul_f32 v[28:29], v[28:29], v[2:3] op_sel_hi:[1,0]
	v_pk_mul_f32 v[30:31], v[30:31], v[2:3] op_sel_hi:[1,0]
	s_waitcnt vmcnt(6)
	v_pk_fma_f32 v[28:29], v[44:45], v[28:29], v[48:49]
	v_pk_fma_f32 v[18:19], v[18:19], v[30:31], v[50:51]
	v_cvt_pk_bf16_f32 v28, v28, v29
	v_pk_mul_f32 v[32:33], v[32:33], v[2:3] op_sel_hi:[1,0]
	v_cvt_pk_bf16_f32 v29, v18, v19
	global_store_dwordx2 v[56:57], v[28:29], off
	v_pk_mul_f32 v[34:35], v[34:35], v[2:3] op_sel_hi:[1,0]
	v_lshl_add_u64 v[44:45], v[52:53], 0, v[12:13]
	v_cmp_lt_i32_e32 vcc, s26, v0
	s_or_b64 s[8:9], vcc, s[8:9]
	s_waitcnt vmcnt(6)
	v_pk_add_f32 v[16:17], v[72:73], 1.0 op_sel_hi:[1,0]
	v_pk_add_f32 v[18:19], v[74:75], 1.0 op_sel_hi:[1,0]
	s_waitcnt vmcnt(5)
	v_pk_fma_f32 v[16:17], v[16:17], v[32:33], v[76:77]
	v_pk_fma_f32 v[18:19], v[18:19], v[34:35], v[78:79]
	v_cvt_pk_bf16_f32 v16, v16, v17
	v_pk_mul_f32 v[34:35], v[36:37], v[2:3] op_sel_hi:[1,0]
	v_cvt_pk_bf16_f32 v17, v18, v19
	global_store_dwordx2 v[56:57], v[16:17], off offset:512
	v_pk_mul_f32 v[36:37], v[38:39], v[2:3] op_sel_hi:[1,0]
	v_lshl_add_u64 v[32:33], v[52:53], 0, v[14:15]
	s_waitcnt vmcnt(5)
	v_pk_add_f32 v[16:17], v[80:81], 1.0 op_sel_hi:[1,0]
	v_pk_add_f32 v[18:19], v[82:83], 1.0 op_sel_hi:[1,0]
	s_waitcnt vmcnt(4)
	v_pk_fma_f32 v[16:17], v[16:17], v[34:35], v[84:85]
	v_pk_fma_f32 v[18:19], v[18:19], v[36:37], v[86:87]
	v_cvt_pk_bf16_f32 v16, v16, v17
	v_pk_mul_f32 v[34:35], v[42:43], v[2:3] op_sel_hi:[1,0]
	v_cvt_pk_bf16_f32 v17, v18, v19
	global_store_dwordx2 v[56:57], v[16:17], off offset:1024
	v_pk_mul_f32 v[32:33], v[40:41], v[2:3] op_sel_hi:[1,0]
	s_waitcnt vmcnt(4)
	v_pk_add_f32 v[16:17], v[88:89], 1.0 op_sel_hi:[1,0]
	v_pk_add_f32 v[18:19], v[90:91], 1.0 op_sel_hi:[1,0]
	s_waitcnt vmcnt(3)
	v_pk_fma_f32 v[16:17], v[32:33], v[16:17], v[92:93]
	v_pk_fma_f32 v[18:19], v[34:35], v[18:19], v[94:95]
	v_cvt_pk_bf16_f32 v16, v16, v17
	s_nop 0
	v_cvt_pk_bf16_f32 v17, v18, v19
	global_store_dwordx2 v[56:57], v[16:17], off offset:1536
	s_andn2_b64 exec, exec, s[8:9]
	s_cbranch_execz .LBB0_59

; __device__ __forceinline__ float bflo(unsigned w) { return __uint_as_float(w << 16); }
; __device__ __forceinline__ float bfhi(unsigned w) { return __uint_as_float(w & 0xffff0000u); }
; __device__ __forceinline__ float wave_sum(float v) {
; #pragma unroll
;     for (int o = 32; o > 0; o >>= 1) v += __shfl_xor(v, o);
;     return v;
; }
; __device__ __forceinline__ void norm_rows_b(const bf16_t* hb, int r_begin, int nrows, int stride, int second_off, const float* modl, int shoff, int scoff, bf16_t* xl) {
;     ...
;     for (int r = r_begin; r < nrows; r += stride) {
;         const int r1 = r + second_off; const bool two = r1 < nrows;
;         u32x4 w[2][2]; float s[2];
; #pragma unroll
;         for (int q = 0; q < 2; ++q) { const bf16_t* xr = hb + (size_t)(q ? (two ? r1 : r) : r) * DM + 8 * lane; w[q][0] = *(const u32x4*)(xr); w[q][1] = *(const u32x4*)(xr + 512); }
;         float v[2][16];
; #pragma unroll
;         for (int q = 0; q < 2; ++q) { float a = 0.f;
; #pragma unroll
;             for (int h = 0; h < 2; ++h)
; #pragma unroll
;                 for (int e = 0; e < 4; ++e) { const float lo = bflo(w[q][h][e]), hi = bfhi(w[q][h][e]); v[q][8 * h + 2 * e] = lo; v[q][8 * h + 2 * e + 1] = hi; a += lo * lo + hi * hi; }
;             s[q] = a; }
; #pragma unroll
;         for (int o = 32; o > 0; o >>= 1) { s[0] += __shfl_xor(s[0], o); s[1] += __shfl_xor(s[1], o); }
; #pragma unroll
;         for (int q = 0; q < 2; ++q) { if (q == 1 && !two) break; const int rr = q ? r1 : r; const int cond = rr < MLAT ? (rr >> 13) : 8; const float* mp = modl + cond * 6144;
;             const float rstd = rsqrtf(s[q] * (1.0f / DM) + EPS);
.LBB0_335:
	v_ashrrev_i32_e32 v13, 31, v12
	v_lshlrev_b64 v[30:31], 11, v[12:13]
	s_waitcnt lgkmcnt(0)
	v_lshl_add_u64 v[10:11], v[2:3], 0, v[30:31]
	global_load_dwordx4 v[22:25], v[10:11], off
	global_load_dwordx4 v[26:29], v[10:11], off offset:1024
	v_min_i32_e32 v7, 0x10000, v12
	v_add_u32_e32 v10, s42, v12
	v_ashrrev_i32_e32 v7, 13, v7
	v_cmp_gt_i32_e32 vcc, s12, v10
	v_mul_i32_i24_e32 v32, 0x1800, v7
	v_ashrrev_i32_e32 v33, 31, v32
	v_cndmask_b32_e32 v12, v12, v10, vcc
	v_ashrrev_i32_e32 v13, 31, v12
	v_lshl_add_u64 v[48:49], v[32:33], 2, s[54:55]
	v_lshlrev_b64 v[12:13], 11, v[12:13]
	v_lshl_add_u64 v[56:57], v[48:49], 0, s[8:9]
	v_lshl_add_u64 v[12:13], v[2:3], 0, v[12:13]
	v_lshl_add_u64 v[40:41], v[56:57], 0, v[0:1]
	global_load_dwordx4 v[32:35], v[12:13], off
	global_load_dwordx4 v[80:83], v[40:41], off offset:2064
	global_load_dwordx4 v[84:87], v[40:41], off offset:2048
	global_load_dwordx4 v[36:39], v[40:41], off
	s_nop 0
	global_load_dwordx4 v[40:43], v[40:41], off offset:16
	s_nop 0
	global_load_dwordx4 v[44:47], v[12:13], off offset:1024
	v_lshl_add_u64 v[12:13], v[48:49], 0, s[10:11]
	v_lshl_add_u64 v[52:53], v[12:13], 0, v[0:1]
	global_load_dwordx4 v[88:91], v[52:53], off offset:2064
	global_load_dwordx4 v[92:95], v[52:53], off offset:2048
	global_load_dwordx4 v[48:51], v[52:53], off offset:16
	s_nop 0
	global_load_dwordx4 v[52:55], v[52:53], off
	v_lshl_add_u64 v[66:67], v[4:5], 0, v[30:31]
	v_lshl_add_u64 v[12:13], v[12:13], 0, v[8:9]
	v_min_i32_e32 v147, 0x10000, v10
	v_ashrrev_i32_e32 v147, 13, v147
	v_mul_i32_i24_e32 v148, 0x1800, v147
	v_ashrrev_i32_e32 v149, 31, v148
	v_lshl_add_u64 v[96:97], v[148:149], 2, s[54:55]
	v_lshl_add_u64 v[98:99], v[96:97], 0, s[8:9]
	v_lshl_add_u64 v[100:101], v[98:99], 0, v[0:1]
	v_lshl_add_u64 v[102:103], v[96:97], 0, s[10:11]
	global_load_dwordx4 v[104:107], v[100:101], off offset:2048
	global_load_dwordx4 v[108:111], v[100:101], off offset:2064
	global_load_dwordx4 v[112:115], v[100:101], off
	global_load_dwordx4 v[116:119], v[100:101], off offset:16
	v_lshl_add_u64 v[120:121], v[102:103], 0, v[0:1]
	global_load_dwordx4 v[122:125], v[120:121], off offset:2048
	global_load_dwordx4 v[126:129], v[120:121], off offset:2064
	global_load_dwordx4 v[130:133], v[120:121], off
	global_load_dwordx4 v[134:137], v[120:121], off offset:16
	s_waitcnt vmcnt(19)
	v_and_b32_e32 v11, 0xffff0000, v22
	v_and_b32_e32 v69, 0xffff0000, v23
	v_lshlrev_b32_e32 v7, 16, v22
	v_lshlrev_b32_e32 v68, 16, v23
	v_and_b32_e32 v71, 0xffff0000, v24
	s_waitcnt vmcnt(18)
	v_lshlrev_b32_e32 v58, 16, v26
	v_and_b32_e32 v60, 0xffff0000, v26
	v_mul_f32_e32 v21, v11, v11
	v_mul_f32_e32 v26, v69, v69
	v_lshlrev_b32_e32 v70, 16, v24
	v_and_b32_e32 v73, 0xffff0000, v25
	v_lshlrev_b32_e32 v59, 16, v27
	v_and_b32_e32 v61, 0xffff0000, v27
	v_mul_f32_e32 v27, v71, v71
	v_fmac_f32_e32 v21, v7, v7
	v_fmac_f32_e32 v26, v68, v68
	v_lshlrev_b32_e32 v72, 16, v25
	v_lshlrev_b32_e32 v62, 16, v28
	v_and_b32_e32 v64, 0xffff0000, v28
	v_mul_f32_e32 v28, v73, v73
	v_fmac_f32_e32 v27, v70, v70
	v_add_f32_e32 v21, v21, v26
	v_pk_mul_f32 v[22:23], v[60:61], v[60:61]
	v_fmac_f32_e32 v28, v72, v72
	v_add_f32_e32 v21, v27, v21
	v_and_b32_e32 v65, 0xffff0000, v29
	v_pk_fma_f32 v[22:23], v[58:59], v[58:59], v[22:23]
	v_add_f32_e32 v21, v28, v21
	v_lshlrev_b32_e32 v63, 16, v29
	v_pk_mul_f32 v[24:25], v[64:65], v[64:65]
	v_add_f32_e32 v21, v22, v21
	v_pk_fma_f32 v[24:25], v[62:63], v[62:63], v[24:25]
	v_add_f32_e32 v21, v23, v21
	v_add_f32_e32 v21, v24, v21
	v_add_f32_e32 v21, v25, v21
	s_waitcnt vmcnt(14)
	v_add_f32_e32 v25, 1.0, v37
	v_lshl_add_u64 v[26:27], v[56:57], 0, v[8:9]
	v_add_f32_e32 v24, 1.0, v36
	v_add_f32_e32 v28, 1.0, v38
	s_waitcnt lgkmcnt(0)
	s_nop 1
	v_add_f32_dpp v21, v21, v21 quad_perm:[1,0,3,2] row_mask:0xf bank_mask:0xf
	s_waitcnt vmcnt(13)
	v_add_f32_e32 v30, 1.0, v40
	v_add_f32_e32 v29, 1.0, v39
	v_add_f32_e32 v31, 1.0, v42
	v_add_f32_e32 v36, 1.0, v43
	s_waitcnt lgkmcnt(0)
	s_nop 1
	v_add_f32_dpp v21, v21, v21 quad_perm:[2,3,0,1] row_mask:0xf bank_mask:0xf
	s_waitcnt lgkmcnt(0)
	s_nop 1
	v_add_f32_dpp v21, v21, v21 row_half_mirror row_mask:0xf bank_mask:0xf
	s_waitcnt lgkmcnt(0)
	s_nop 1
	v_add_f32_dpp v22, v21, v21 row_mirror row_mask:0xf bank_mask:0xf
	v_lshlrev_b32_e32 v21, 16, v32
	s_waitcnt lgkmcnt(0)
	s_nop 1
	v_add_f32_dpp v22, v22, v22 row_bcast:15 row_mask:0xa bank_mask:0xf
	s_waitcnt lgkmcnt(0)
	s_nop 1
	v_add_f32_dpp v22, v22, v22 row_bcast:31 row_mask:0xc bank_mask:0xf
	s_nop 0
	v_readlane_b32 s100, v22, 63
	s_nop 1
	v_mov_b32_e32 v22, s100
	v_fmamk_f32 v22, v22, 0x3a800000, v20
	v_mul_f32_e32 v23, 0x4b800000, v22
	v_cmp_gt_f32_e64 s[6:7], s13, v22
	s_nop 1
	v_cndmask_b32_e64 v22, v22, v23, s[6:7]
	v_rsq_f32_e32 v22, v22
	v_add_f32_e32 v23, 1.0, v41
	v_mul_f32_e32 v37, 0x45800000, v22
	v_cndmask_b32_e64 v56, v22, v37, s[6:7]
	v_mul_f32_e32 v7, v56, v7
	v_mul_f32_e32 v11, v56, v11
	v_mul_f32_e32 v22, v56, v68
	v_mul_f32_e32 v38, v56, v70
	v_mul_f32_e32 v37, v56, v69
	v_mul_f32_e32 v39, v56, v71
	v_mul_f32_e32 v40, v56, v72
	v_mul_f32_e32 v41, v56, v73
	s_waitcnt vmcnt(8)
; __device__ __forceinline__ unsigned cvt_pk_bf16(float lo, float hi) { unsigned r; asm volatile("v_cvt_pk_bf16_f32 %0, %1, %2" : "=v"(r) : "v"(lo), "v"(hi)); return r; }
; __device__ __forceinline__ float bflo(unsigned w) { return __uint_as_float(w << 16); }
; __device__ __forceinline__ float bfhi(unsigned w) { return __uint_as_float(w & 0xffff0000u); }
; __device__ __forceinline__ float wave_sum(float v) {
; #pragma unroll
;     for (int o = 32; o > 0; o >>= 1) v += __shfl_xor(v, o);
;     return v;
; }
; __device__ __forceinline__ void norm_rows_b(const bf16_t* hb, int r_begin, int nrows, int stride, int second_off, const float* modl, int shoff, int scoff, bf16_t* xl) {
;     ...
;         for (int q = 0; q < 2; ++q) { float a = 0.f;
; #pragma unroll
;             for (int h = 0; h < 2; ++h)
; #pragma unroll
;                 for (int e = 0; e < 4; ++e) { const float lo = bflo(w[q][h][e]), hi = bfhi(w[q][h][e]); v[q][8 * h + 2 * e] = lo; v[q][8 * h + 2 * e + 1] = hi; a += lo * lo + hi * hi; }
;             s[q] = a; }
; #pragma unroll
;         for (int o = 32; o > 0; o >>= 1) { s[0] += __shfl_xor(s[0], o); s[1] += __shfl_xor(s[1], o); }
; #pragma unroll
;         for (int q = 0; q < 2; ++q) { if (q == 1 && !two) break; const int rr = q ? r1 : r; const int cond = rr < MLAT ? (rr >> 13) : 8; const float* mp = modl + cond * 6144;
;             const float rstd = rsqrtf(s[q] * (1.0f / DM) + EPS);
; #pragma unroll
;             for (int h = 0; h < 2; ++h) { const int col = 8 * lane + 512 * h; const f32x4 sc0 = *(const f32x4*)(mp + scoff + col), sc1 = *(const f32x4*)(mp + scoff + col + 4), sh0 = *(const f32x4*)(mp + shoff + col), sh1 = *(const f32x4*)(mp + shoff + col + 4);
;                 u32x4 o;
;                 o.x = cvt_pk_bf16(v[q][8 * h + 0] * rstd * (sc0[0] + 1.0f) + sh0[0], v[q][8 * h + 1] * rstd * (sc0[1] + 1.0f) + sh0[1]);
;                 o.y = cvt_pk_bf16(v[q][8 * h + 2] * rstd * (sc0[2] + 1.0f) + sh0[2], v[q][8 * h + 3] * rstd * (sc0[3] + 1.0f) + sh0[3]);
;                 o.z = cvt_pk_bf16(v[q][8 * h + 4] * rstd * (sc1[0] + 1.0f) + sh1[0], v[q][8 * h + 5] * rstd * (sc1[1] + 1.0f) + sh1[1]);
;                 o.w = cvt_pk_bf16(v[q][8 * h + 6] * rstd * (sc1[2] + 1.0f) + sh1[2], v[q][8 * h + 7] * rstd * (sc1[3] + 1.0f) + sh1[3]);
;                 *(u32x4*)(xl + (size_t)rr * DM + col) = o; } }
	v_fma_f32 v7, v24, v7, v52
	v_fma_f32 v11, v25, v11, v53
	v_fma_f32 v24, v28, v22, v54
	v_fma_f32 v25, v30, v38, v48
	v_fmac_f32_e32 v55, v29, v37
	v_fma_f32 v28, v23, v39, v49
	v_fma_f32 v29, v31, v40, v50
	v_fmac_f32_e32 v51, v36, v41
	v_cvt_pk_bf16_f32 v22, v7, v11
	v_cvt_pk_bf16_f32 v23, v24, v55
	v_cvt_pk_bf16_f32 v24, v25, v28
	v_cvt_pk_bf16_f32 v25, v29, v51
	global_store_dwordx4 v[66:67], v[22:25], off
	v_and_b32_e32 v28, 0xffff0000, v32
	v_and_b32_e32 v30, 0xffff0000, v33
	v_lshlrev_b32_e32 v29, 16, v33
	v_and_b32_e32 v32, 0xffff0000, v34
	v_mul_f32_e32 v7, v28, v28
	v_mul_f32_e32 v11, v30, v30
	v_lshlrev_b32_e32 v31, 16, v34
	v_lshlrev_b32_e32 v33, 16, v35
	v_and_b32_e32 v34, 0xffff0000, v35
	v_mul_f32_e32 v35, v32, v32
	v_fmac_f32_e32 v7, v21, v21
	v_fmac_f32_e32 v11, v29, v29
	v_lshlrev_b32_e32 v27, 16, v44
	v_and_b32_e32 v26, 0xffff0000, v44
	v_mul_f32_e32 v44, v34, v34
	v_fmac_f32_e32 v35, v31, v31
	v_add_f32_e32 v7, v7, v11
	v_lshlrev_b32_e32 v25, 16, v45
	v_and_b32_e32 v24, 0xffff0000, v45
	v_mul_f32_e32 v45, v26, v26
	v_fmac_f32_e32 v44, v33, v33
	v_add_f32_e32 v7, v35, v7
	v_lshlrev_b32_e32 v23, 16, v46
	v_and_b32_e32 v22, 0xffff0000, v46
	v_mul_f32_e32 v46, v24, v24
	v_fmac_f32_e32 v45, v27, v27
	v_add_f32_e32 v7, v44, v7
	v_lshlrev_b32_e32 v13, 16, v47
	v_and_b32_e32 v12, 0xffff0000, v47
	v_mul_f32_e32 v47, v22, v22
	v_fmac_f32_e32 v46, v25, v25
	v_add_f32_e32 v7, v45, v7
	v_mul_f32_e32 v57, v12, v12
	v_fmac_f32_e32 v47, v23, v23
	v_add_f32_e32 v7, v46, v7
	v_fmac_f32_e32 v57, v13, v13
	v_add_f32_e32 v7, v47, v7
	v_add_f32_e32 v7, v57, v7
	v_mul_f32_e32 v35, v56, v58
	v_mul_f32_e32 v44, v56, v60
	v_mul_f32_e32 v45, v56, v59
	v_mul_f32_e32 v46, v56, v61
	s_waitcnt lgkmcnt(0)
	s_nop 1
	v_add_f32_dpp v7, v7, v7 quad_perm:[1,0,3,2] row_mask:0xf bank_mask:0xf
	v_mul_f32_e32 v47, v56, v62
	v_mul_f32_e32 v57, v56, v64
	v_mul_f32_e32 v58, v56, v63
	v_mul_f32_e32 v56, v56, v65
	s_waitcnt lgkmcnt(0)
	s_nop 1
	v_add_f32_dpp v7, v7, v7 quad_perm:[2,3,0,1] row_mask:0xf bank_mask:0xf
	s_waitcnt lgkmcnt(0)
	s_nop 1
	v_add_f32_dpp v7, v7, v7 row_half_mirror row_mask:0xf bank_mask:0xf
	s_waitcnt lgkmcnt(0)
	s_nop 1
	v_add_f32_dpp v7, v7, v7 row_mirror row_mask:0xf bank_mask:0xf
	s_waitcnt lgkmcnt(0)
	s_nop 1
	v_add_f32_dpp v7, v7, v7 row_bcast:15 row_mask:0xa bank_mask:0xf
	s_waitcnt vmcnt(17)
	v_add_f32_e32 v36, 1.0, v80
	s_waitcnt vmcnt(16)
	v_add_f32_e32 v40, 1.0, v84
	v_add_f32_e32 v41, 1.0, v85
	v_add_f32_e32 v42, 1.0, v86
	v_add_f32_e32 v43, 1.0, v87
	v_add_f32_e32 v37, 1.0, v81
	v_add_f32_e32 v38, 1.0, v82
	v_add_f32_e32 v39, 1.0, v83
	s_waitcnt vmcnt(11)
	v_fma_f32 v35, v40, v35, v92
	v_fma_f32 v40, v41, v44, v93
	v_fma_f32 v41, v42, v45, v94
	v_fma_f32 v55, v43, v46, v95
	v_fma_f32 v42, v47, v36, v88
	v_fma_f32 v43, v57, v37, v89
	v_fma_f32 v44, v58, v38, v90
	v_fma_f32 v51, v56, v39, v91
	v_cvt_pk_bf16_f32 v36, v35, v40
	v_cvt_pk_bf16_f32 v37, v41, v55
	v_cvt_pk_bf16_f32 v38, v42, v43
	v_cvt_pk_bf16_f32 v39, v44, v51
	global_store_dwordx4 v[66:67], v[36:39], off offset:1024
	s_and_saveexec_b64 s[6:7], vcc
	s_cbranch_execz .LBB0_334
	s_waitcnt lgkmcnt(0)
	v_mov_b32_e32 v35, v7
	s_nop 1
	v_add_f32_dpp v35, v35, v35 row_bcast:31 row_mask:0xc bank_mask:0xf
	s_nop 0
	v_readlane_b32 s101, v35, 63
	s_nop 1
	v_mov_b32_e32 v35, s101
	v_fmamk_f32 v35, v35, 0x3a800000, v20
	v_mul_f32_e32 v56, 0x4b800000, v35
	v_cmp_gt_f32_e32 vcc, s13, v35
	v_ashrrev_i32_e32 v11, 31, v10
	v_mov_b32_e32 v7, v1
	v_cndmask_b32_e32 v35, v35, v56, vcc
	v_rsq_f32_e32 v35, v35
	v_lshlrev_b64 v[56:57], 11, v[10:11]
	v_lshl_add_u64 v[56:57], v[4:5], 0, v[56:57]
	v_lshl_add_u64 v[52:53], v[98:99], 0, v[6:7]
	v_mul_f32_e32 v11, 0x45800000, v35
	v_cndmask_b32_e32 v11, v35, v11, vcc
	v_mul_f32_e32 v28, v11, v28
	v_mul_f32_e32 v29, v11, v29
	v_mul_f32_e32 v30, v11, v30
	v_mul_f32_e32 v31, v11, v31
	v_mul_f32_e32 v32, v11, v32
	v_mul_f32_e32 v21, v11, v21
	v_mul_f32_e32 v33, v11, v33
	v_mul_f32_e32 v34, v11, v34
	v_mul_f32_e32 v25, v11, v25
	v_mul_f32_e32 v24, v11, v24
	v_mul_f32_e32 v23, v11, v23
	v_mul_f32_e32 v22, v11, v22
	v_mul_f32_e32 v13, v11, v13
	s_waitcnt vmcnt(7)
	v_add_f32_e32 v35, 1.0, v112
	v_add_f32_e32 v36, 1.0, v113
	v_add_f32_e32 v37, 1.0, v114
	v_add_f32_e32 v38, 1.0, v115
	s_waitcnt vmcnt(6)
	v_add_f32_e32 v39, 1.0, v116
	v_add_f32_e32 v40, 1.0, v117
	v_add_f32_e32 v41, 1.0, v118
	v_add_f32_e32 v42, 1.0, v119
	s_waitcnt vmcnt(3)
	v_fma_f32 v28, v28, v36, v131
	v_fma_f32 v29, v29, v37, v132
	v_fma_f32 v47, v30, v38, v133
	s_waitcnt vmcnt(2)
	v_fma_f32 v30, v31, v39, v134
	v_fma_f32 v31, v32, v40, v135
	v_fma_f32 v21, v21, v35, v130
	v_fma_f32 v32, v33, v41, v136
	v_fma_f32 v51, v34, v42, v137
	v_cvt_pk_bf16_f32 v28, v21, v28
	v_cvt_pk_bf16_f32 v29, v29, v47
	v_cvt_pk_bf16_f32 v30, v30, v31
	v_cvt_pk_bf16_f32 v31, v32, v51
	global_store_dwordx4 v[56:57], v[28:31], off
	s_nop 0
	v_lshl_add_u64 v[40:41], v[102:103], 0, v[6:7]
	s_nop 0
	v_mul_f32_e32 v7, v11, v27
	v_mul_f32_e32 v21, v11, v26
	v_mul_f32_e32 v11, v11, v12
	s_waitcnt vmcnt(10)
	v_add_f32_e32 v12, 1.0, v104
	v_add_f32_e32 v26, 1.0, v105
	v_add_f32_e32 v27, 1.0, v106
	v_add_f32_e32 v28, 1.0, v107
	s_waitcnt vmcnt(9)
	v_add_f32_e32 v29, 1.0, v108
	v_add_f32_e32 v30, 1.0, v109
	v_add_f32_e32 v31, 1.0, v110
	v_add_f32_e32 v32, 1.0, v111
	s_waitcnt vmcnt(6)
	v_fma_f32 v7, v7, v12, v122
	v_fma_f32 v12, v21, v26, v123
	v_fma_f32 v21, v25, v27, v124
	v_fma_f32 v39, v24, v28, v125
	s_waitcnt vmcnt(5)
	v_fma_f32 v24, v23, v29, v126
	v_fma_f32 v25, v22, v30, v127
	v_fma_f32 v13, v13, v31, v128
	v_fma_f32 v43, v11, v32, v129
	v_cvt_pk_bf16_f32 v22, v7, v12
	v_cvt_pk_bf16_f32 v23, v21, v39
	v_cvt_pk_bf16_f32 v24, v24, v25
	v_cvt_pk_bf16_f32 v25, v13, v43
	global_store_dwordx4 v[56:57], v[22:25], off offset:1024
	s_branch .LBB0_334

; __device__ __forceinline__ float bflo(unsigned w) { return __uint_as_float(w << 16); }
; __device__ __forceinline__ float bfhi(unsigned w) { return __uint_as_float(w & 0xffff0000u); }
; __device__ __forceinline__ float wave_sum(float v) {
; #pragma unroll
;     for (int o = 32; o > 0; o >>= 1) v += __shfl_xor(v, o);
;     return v;
; }
; __device__ __forceinline__ void norm_rows_b(const bf16_t* hb, int r_begin, int nrows, int stride, int second_off, const float* modl, int shoff, int scoff, bf16_t* xl) {
;     ...
;     for (int r = r_begin; r < nrows; r += stride) {
;         const int r1 = r + second_off; const bool two = r1 < nrows;
;         u32x4 w[2][2]; float s[2];
; #pragma unroll
;         for (int q = 0; q < 2; ++q) { const bf16_t* xr = hb + (size_t)(q ? (two ? r1 : r) : r) * DM + 8 * lane; w[q][0] = *(const u32x4*)(xr); w[q][1] = *(const u32x4*)(xr + 512); }
;         float v[2][16];
; #pragma unroll
;         for (int q = 0; q < 2; ++q) { float a = 0.f;
; #pragma unroll
;             for (int h = 0; h < 2; ++h)
; #pragma unroll
;                 for (int e = 0; e < 4; ++e) { const float lo = bflo(w[q][h][e]), hi = bfhi(w[q][h][e]); v[q][8 * h + 2 * e] = lo; v[q][8 * h + 2 * e + 1] = hi; a += lo * lo + hi * hi; }
;             s[q] = a; }
; #pragma unroll
;         for (int o = 32; o > 0; o >>= 1) { s[0] += __shfl_xor(s[0], o); s[1] += __shfl_xor(s[1], o); }
; #pragma unroll
;         for (int q = 0; q < 2; ++q) { if (q == 1 && !two) break; const int rr = q ? r1 : r; const int cond = rr < MLAT ? (rr >> 13) : 8; const float* mp = modl + cond * 6144;
;             const float rstd = rsqrtf(s[q] * (1.0f / DM) + EPS);
.LBB0_586:
	v_ashrrev_i32_e32 v13, 31, v12
	v_lshlrev_b64 v[56:57], 11, v[12:13]
	s_waitcnt lgkmcnt(0)
	v_lshl_add_u64 v[10:11], v[2:3], 0, v[56:57]
	global_load_dwordx4 v[14:17], v[10:11], off
	global_load_dwordx4 v[28:31], v[10:11], off offset:1024
	v_min_i32_e32 v7, 0x10000, v12
	v_add_u32_e32 v10, s28, v12
	v_ashrrev_i32_e32 v7, 13, v7
	v_cmp_gt_i32_e32 vcc, s20, v10
	v_mul_i32_i24_e32 v18, 0x1800, v7
	v_ashrrev_i32_e32 v19, 31, v18
	v_cndmask_b32_e32 v12, v12, v10, vcc
	v_ashrrev_i32_e32 v13, 31, v12
	v_lshl_add_u64 v[18:19], v[18:19], 2, s[16:17]
	v_lshlrev_b64 v[12:13], 11, v[12:13]
	v_lshl_add_u64 v[58:59], v[18:19], 0, s[14:15]
	v_lshl_add_u64 v[12:13], v[2:3], 0, v[12:13]
	v_lshl_add_u64 v[40:41], v[58:59], 0, v[0:1]
	global_load_dwordx4 v[32:35], v[12:13], off
	global_load_dwordx4 v[80:83], v[40:41], off offset:2064
	global_load_dwordx4 v[84:87], v[40:41], off offset:2048
	global_load_dwordx4 v[36:39], v[40:41], off
	s_nop 0
	global_load_dwordx4 v[40:43], v[40:41], off offset:16
	s_nop 0
	global_load_dwordx4 v[44:47], v[12:13], off offset:1024
	v_lshl_add_u64 v[60:61], v[18:19], 0, v[0:1]
	global_load_dwordx4 v[88:91], v[60:61], off offset:2064
	global_load_dwordx4 v[92:95], v[60:61], off offset:2048
	global_load_dwordx4 v[48:51], v[60:61], off offset:16
	global_load_dwordx4 v[52:55], v[60:61], off
	v_min_i32_e32 v148, 0x10000, v10
	v_ashrrev_i32_e32 v148, 13, v148
	v_mul_i32_i24_e32 v148, 0x1800, v148
	v_ashrrev_i32_e32 v149, 31, v148
	v_lshl_add_u64 v[96:97], v[148:149], 2, s[16:17]
	v_lshl_add_u64 v[98:99], v[96:97], 0, s[14:15]
	v_lshl_add_u64 v[100:101], v[98:99], 0, v[0:1]
	global_load_dwordx4 v[102:105], v[100:101], off offset:2048
	global_load_dwordx4 v[106:109], v[100:101], off offset:2064
	global_load_dwordx4 v[110:113], v[100:101], off
	global_load_dwordx4 v[114:117], v[100:101], off offset:16
	v_lshl_add_u64 v[118:119], v[96:97], 0, v[0:1]
	global_load_dwordx4 v[120:123], v[118:119], off offset:2048
	global_load_dwordx4 v[124:127], v[118:119], off offset:2064
	global_load_dwordx4 v[128:131], v[118:119], off
	global_load_dwordx4 v[132:135], v[118:119], off offset:16
	s_waitcnt vmcnt(19)
	v_and_b32_e32 v11, 0xffff0000, v14
	v_and_b32_e32 v63, 0xffff0000, v15
	v_lshlrev_b32_e32 v7, 16, v14
	v_lshlrev_b32_e32 v62, 16, v15
	v_and_b32_e32 v67, 0xffff0000, v16
	v_mul_f32_e32 v27, v11, v11
	v_mul_f32_e32 v64, v63, v63
	v_lshlrev_b32_e32 v66, 16, v16
	v_and_b32_e32 v69, 0xffff0000, v17
	v_mul_f32_e32 v65, v67, v67
	v_fmac_f32_e32 v27, v7, v7
	v_fmac_f32_e32 v64, v62, v62
	v_lshlrev_b32_e32 v68, 16, v17
	s_waitcnt vmcnt(18)
	v_and_b32_e32 v17, 0xffff0000, v29
	v_and_b32_e32 v16, 0xffff0000, v28
	v_mul_f32_e32 v70, v69, v69
	v_fmac_f32_e32 v65, v66, v66
	v_add_f32_e32 v27, v27, v64
	v_lshlrev_b32_e32 v19, 16, v29
	v_lshlrev_b32_e32 v18, 16, v28
	v_pk_mul_f32 v[28:29], v[16:17], v[16:17]
	v_fmac_f32_e32 v70, v68, v68
	v_add_f32_e32 v27, v65, v27
	v_and_b32_e32 v13, 0xffff0000, v31
	v_and_b32_e32 v12, 0xffff0000, v30
	v_pk_fma_f32 v[28:29], v[18:19], v[18:19], v[28:29]
	v_add_f32_e32 v27, v70, v27
	v_lshlrev_b32_e32 v15, 16, v31
	v_lshlrev_b32_e32 v14, 16, v30
	v_pk_mul_f32 v[30:31], v[12:13], v[12:13]
	v_add_f32_e32 v27, v28, v27
	v_pk_fma_f32 v[30:31], v[14:15], v[14:15], v[30:31]
	v_add_f32_e32 v27, v29, v27
	v_add_f32_e32 v27, v30, v27
	v_add_f32_e32 v27, v31, v27
	s_waitcnt vmcnt(14)
	v_add_f32_e32 v30, 1.0, v36
	v_add_f32_e32 v36, 1.0, v38
	s_waitcnt vmcnt(13)
	v_add_f32_e32 v38, 1.0, v40
	v_add_f32_e32 v40, 1.0, v43
	s_waitcnt lgkmcnt(0)
	s_nop 1
	v_add_f32_dpp v27, v27, v27 quad_perm:[1,0,3,2] row_mask:0xf bank_mask:0xf
	v_add_f32_e32 v31, 1.0, v37
	v_add_f32_e32 v37, 1.0, v39
	v_add_f32_e32 v39, 1.0, v42
	v_lshl_add_u64 v[64:65], v[4:5], 0, v[56:57]
	s_waitcnt lgkmcnt(0)
	s_nop 1
	v_add_f32_dpp v27, v27, v27 quad_perm:[2,3,0,1] row_mask:0xf bank_mask:0xf
	v_lshl_add_u64 v[56:57], v[58:59], 0, v[8:9]
	s_waitcnt lgkmcnt(0)
	s_nop 1
	v_add_f32_dpp v27, v27, v27 row_half_mirror row_mask:0xf bank_mask:0xf
	s_waitcnt lgkmcnt(0)
	s_nop 1
	v_add_f32_dpp v28, v27, v27 row_mirror row_mask:0xf bank_mask:0xf
	v_lshlrev_b32_e32 v27, 16, v32
	s_waitcnt lgkmcnt(0)
	s_nop 1
	v_add_f32_dpp v28, v28, v28 row_bcast:15 row_mask:0xa bank_mask:0xf
	s_waitcnt lgkmcnt(0)
	s_nop 1
	v_add_f32_dpp v28, v28, v28 row_bcast:31 row_mask:0xc bank_mask:0xf
	s_nop 0
	v_readlane_b32 s100, v28, 63
	s_nop 1
	v_mov_b32_e32 v28, s100
	v_fmamk_f32 v28, v28, 0x3a800000, v26
	v_mul_f32_e32 v29, 0x4b800000, v28
	v_cmp_gt_f32_e64 s[38:39], s21, v28
	s_nop 1
	v_cndmask_b32_e64 v28, v28, v29, s[38:39]
	v_rsq_f32_e32 v28, v28
	v_add_f32_e32 v29, 1.0, v41
	v_mul_f32_e32 v41, 0x45800000, v28
	v_cndmask_b32_e64 v43, v28, v41, s[38:39]
	v_mul_f32_e32 v7, v43, v7
	v_mul_f32_e32 v11, v43, v11
	v_mul_f32_e32 v28, v43, v62
	v_mul_f32_e32 v42, v43, v66
	v_mul_f32_e32 v41, v43, v63
	v_mul_f32_e32 v58, v43, v67
	v_mul_f32_e32 v59, v43, v68
	v_mul_f32_e32 v62, v43, v69
	s_waitcnt vmcnt(8)
; __device__ __forceinline__ unsigned cvt_pk_bf16(float lo, float hi) { unsigned r; asm volatile("v_cvt_pk_bf16_f32 %0, %1, %2" : "=v"(r) : "v"(lo), "v"(hi)); return r; }
; __device__ __forceinline__ float bflo(unsigned w) { return __uint_as_float(w << 16); }
; __device__ __forceinline__ float bfhi(unsigned w) { return __uint_as_float(w & 0xffff0000u); }
; __device__ __forceinline__ float wave_sum(float v) {
; #pragma unroll
;     for (int o = 32; o > 0; o >>= 1) v += __shfl_xor(v, o);
;     return v;
; }
; __device__ __forceinline__ void norm_rows_b(const bf16_t* hb, int r_begin, int nrows, int stride, int second_off, const float* modl, int shoff, int scoff, bf16_t* xl) {
;     ...
;         for (int q = 0; q < 2; ++q) { float a = 0.f;
; #pragma unroll
;             for (int h = 0; h < 2; ++h)
; #pragma unroll
;                 for (int e = 0; e < 4; ++e) { const float lo = bflo(w[q][h][e]), hi = bfhi(w[q][h][e]); v[q][8 * h + 2 * e] = lo; v[q][8 * h + 2 * e + 1] = hi; a += lo * lo + hi * hi; }
;             s[q] = a; }
; #pragma unroll
;         for (int o = 32; o > 0; o >>= 1) { s[0] += __shfl_xor(s[0], o); s[1] += __shfl_xor(s[1], o); }
; #pragma unroll
;         for (int q = 0; q < 2; ++q) { if (q == 1 && !two) break; const int rr = q ? r1 : r; const int cond = rr < MLAT ? (rr >> 13) : 8; const float* mp = modl + cond * 6144;
;             const float rstd = rsqrtf(s[q] * (1.0f / DM) + EPS);
; #pragma unroll
;             for (int h = 0; h < 2; ++h) { const int col = 8 * lane + 512 * h; const f32x4 sc0 = *(const f32x4*)(mp + scoff + col), sc1 = *(const f32x4*)(mp + scoff + col + 4), sh0 = *(const f32x4*)(mp + shoff + col), sh1 = *(const f32x4*)(mp + shoff + col + 4);
;                 u32x4 o;
;                 o.x = cvt_pk_bf16(v[q][8 * h + 0] * rstd * (sc0[0] + 1.0f) + sh0[0], v[q][8 * h + 1] * rstd * (sc0[1] + 1.0f) + sh0[1]);
;                 o.y = cvt_pk_bf16(v[q][8 * h + 2] * rstd * (sc0[2] + 1.0f) + sh0[2], v[q][8 * h + 3] * rstd * (sc0[3] + 1.0f) + sh0[3]);
;                 o.z = cvt_pk_bf16(v[q][8 * h + 4] * rstd * (sc1[0] + 1.0f) + sh1[0], v[q][8 * h + 5] * rstd * (sc1[1] + 1.0f) + sh1[1]);
;                 o.w = cvt_pk_bf16(v[q][8 * h + 6] * rstd * (sc1[2] + 1.0f) + sh1[2], v[q][8 * h + 7] * rstd * (sc1[3] + 1.0f) + sh1[3]);
;                 *(u32x4*)(xl + (size_t)rr * DM + col) = o; } }
	v_fma_f32 v7, v30, v7, v52
	v_fma_f32 v11, v31, v11, v53
	v_fma_f32 v30, v36, v28, v54
	v_fma_f32 v31, v38, v42, v48
	v_fmac_f32_e32 v55, v37, v41
	v_fma_f32 v36, v29, v58, v49
	v_fma_f32 v37, v39, v59, v50
	v_fmac_f32_e32 v51, v40, v62
	v_cvt_pk_bf16_f32 v28, v7, v11
	v_cvt_pk_bf16_f32 v29, v30, v55
	v_cvt_pk_bf16_f32 v30, v31, v36
	v_cvt_pk_bf16_f32 v31, v37, v51
	global_store_dwordx4 v[64:65], v[28:31], off
	s_nop 0
	s_nop 0
	v_and_b32_e32 v28, 0xffff0000, v32
	v_and_b32_e32 v38, 0xffff0000, v33
	v_lshlrev_b32_e32 v37, 16, v33
	v_and_b32_e32 v40, 0xffff0000, v34
	v_mul_f32_e32 v7, v28, v28
	v_mul_f32_e32 v11, v38, v38
	v_lshlrev_b32_e32 v39, 16, v34
	v_lshlrev_b32_e32 v41, 16, v35
	v_and_b32_e32 v42, 0xffff0000, v35
	v_lshlrev_b32_e32 v36, 16, v44
	v_and_b32_e32 v35, 0xffff0000, v44
	v_mul_f32_e32 v44, v40, v40
	v_fmac_f32_e32 v7, v27, v27
	v_fmac_f32_e32 v11, v37, v37
	v_lshlrev_b32_e32 v34, 16, v45
	v_and_b32_e32 v33, 0xffff0000, v45
	v_mul_f32_e32 v45, v42, v42
	v_fmac_f32_e32 v44, v39, v39
	v_add_f32_e32 v7, v7, v11
	v_lshlrev_b32_e32 v32, 16, v46
	v_and_b32_e32 v31, 0xffff0000, v46
	v_mul_f32_e32 v46, v35, v35
	v_fmac_f32_e32 v45, v41, v41
	v_add_f32_e32 v7, v44, v7
	v_lshlrev_b32_e32 v30, 16, v47
	v_and_b32_e32 v29, 0xffff0000, v47
	v_mul_f32_e32 v47, v33, v33
	v_fmac_f32_e32 v46, v36, v36
	v_add_f32_e32 v7, v45, v7
	v_mul_f32_e32 v66, v31, v31
	v_fmac_f32_e32 v47, v34, v34
	v_add_f32_e32 v7, v46, v7
	v_mul_f32_e32 v67, v29, v29
	v_fmac_f32_e32 v66, v32, v32
	v_add_f32_e32 v7, v47, v7
	v_fmac_f32_e32 v67, v30, v30
	v_add_f32_e32 v7, v66, v7
	v_add_f32_e32 v7, v67, v7
	v_mul_f32_e32 v14, v43, v14
	v_mul_f32_e32 v15, v43, v15
	v_mul_f32_e32 v18, v43, v18
	v_mul_f32_e32 v16, v43, v16
	s_waitcnt lgkmcnt(0)
	s_nop 1
	v_add_f32_dpp v7, v7, v7 quad_perm:[1,0,3,2] row_mask:0xf bank_mask:0xf
	v_mul_f32_e32 v19, v43, v19
	v_mul_f32_e32 v17, v43, v17
	v_mul_f32_e32 v12, v43, v12
	v_mul_f32_e32 v13, v43, v13
	s_waitcnt lgkmcnt(0)
	s_nop 1
	v_add_f32_dpp v7, v7, v7 quad_perm:[2,3,0,1] row_mask:0xf bank_mask:0xf
	s_waitcnt lgkmcnt(0)
	s_nop 1
	v_add_f32_dpp v7, v7, v7 row_half_mirror row_mask:0xf bank_mask:0xf
	s_waitcnt lgkmcnt(0)
	s_nop 1
	v_add_f32_dpp v7, v7, v7 row_mirror row_mask:0xf bank_mask:0xf
	s_waitcnt lgkmcnt(0)
	s_nop 1
	v_add_f32_dpp v7, v7, v7 row_bcast:15 row_mask:0xa bank_mask:0xf
	s_waitcnt vmcnt(17)
	v_add_f32_e32 v47, 1.0, v80
	v_add_f32_e32 v48, 1.0, v81
	v_add_f32_e32 v49, 1.0, v82
	s_waitcnt vmcnt(16)
	v_add_f32_e32 v43, 1.0, v84
	v_add_f32_e32 v44, 1.0, v85
	v_add_f32_e32 v45, 1.0, v86
	v_add_f32_e32 v46, 1.0, v87
	v_add_f32_e32 v50, 1.0, v83
	s_waitcnt vmcnt(12)
	v_fma_f32 v14, v14, v47, v88
	v_fma_f32 v15, v15, v49, v90
	s_waitcnt vmcnt(11)
	v_fma_f32 v18, v43, v18, v92
	v_fma_f32 v16, v44, v16, v93
	v_fma_f32 v19, v45, v19, v94
	v_fma_f32 v63, v46, v17, v95
	v_fma_f32 v17, v12, v48, v89
	v_fma_f32 v59, v13, v50, v91
	v_cvt_pk_bf16_f32 v12, v18, v16
	v_cvt_pk_bf16_f32 v13, v19, v63
	v_cvt_pk_bf16_f32 v14, v14, v17
	v_cvt_pk_bf16_f32 v15, v15, v59
	global_store_dwordx4 v[64:65], v[12:15], off offset:1024
	s_and_saveexec_b64 s[18:19], vcc
	s_cbranch_execz .LBB0_585
	s_waitcnt lgkmcnt(0)
	v_mov_b32_e32 v43, v7
	s_nop 1
	v_add_f32_dpp v43, v43, v43 row_bcast:31 row_mask:0xc bank_mask:0xf
	s_nop 0
	v_readlane_b32 s101, v43, 63
	s_nop 1
	v_mov_b32_e32 v43, s101
	v_fmamk_f32 v43, v43, 0x3a800000, v26
	v_mul_f32_e32 v56, 0x4b800000, v43
	v_cmp_gt_f32_e32 vcc, s21, v43
	v_mov_b32_e32 v7, v1
	v_lshl_add_u64 v[52:53], v[98:99], 0, v[6:7]
	v_cndmask_b32_e32 v43, v43, v56, vcc
	v_rsq_f32_e32 v43, v43
	v_ashrrev_i32_e32 v11, 31, v10
	v_lshlrev_b64 v[56:57], 11, v[10:11]
	v_lshl_add_u64 v[56:57], v[4:5], 0, v[56:57]
	v_mul_f32_e32 v7, 0x45800000, v43
	v_cndmask_b32_e32 v7, v43, v7, vcc
	v_mul_f32_e32 v11, v7, v27
	v_mul_f32_e32 v27, v7, v28
	v_mul_f32_e32 v28, v7, v37
	v_mul_f32_e32 v37, v7, v38
	v_mul_f32_e32 v38, v7, v39
	v_mul_f32_e32 v39, v7, v40
	v_mul_f32_e32 v40, v7, v41
	v_mul_f32_e32 v41, v7, v42
	v_mul_f32_e32 v33, v7, v33
	v_mul_f32_e32 v32, v7, v32
	v_mul_f32_e32 v31, v7, v31
	v_mul_f32_e32 v30, v7, v30
	s_waitcnt vmcnt(7)
	v_add_f32_e32 v12, 1.0, v110
	v_add_f32_e32 v13, 1.0, v111
	v_add_f32_e32 v14, 1.0, v112
	v_add_f32_e32 v15, 1.0, v113
	s_waitcnt vmcnt(6)
	v_add_f32_e32 v16, 1.0, v114
	v_add_f32_e32 v17, 1.0, v115
	v_add_f32_e32 v18, 1.0, v116
	v_add_f32_e32 v19, 1.0, v117
	s_waitcnt vmcnt(3)
	v_fma_f32 v11, v11, v12, v128
	v_fma_f32 v12, v27, v13, v129
	v_fma_f32 v13, v28, v14, v130
	v_fma_f32 v47, v37, v15, v131
	s_waitcnt vmcnt(2)
	v_fma_f32 v14, v38, v16, v132
	v_fma_f32 v15, v39, v17, v133
	v_fma_f32 v16, v40, v18, v134
	v_fma_f32 v51, v41, v19, v135
	v_cvt_pk_bf16_f32 v12, v11, v12
	v_cvt_pk_bf16_f32 v13, v13, v47
	v_cvt_pk_bf16_f32 v14, v14, v15
	v_cvt_pk_bf16_f32 v15, v16, v51
	global_store_dwordx4 v[56:57], v[12:15], off
	s_nop 0
	v_mul_f32_e32 v11, v7, v36
	v_mul_f32_e32 v27, v7, v35
	v_mul_f32_e32 v28, v7, v34
	v_mul_f32_e32 v7, v7, v29
	s_waitcnt vmcnt(10)
	v_add_f32_e32 v12, 1.0, v102
	v_add_f32_e32 v13, 1.0, v103
	v_add_f32_e32 v14, 1.0, v104
	v_add_f32_e32 v15, 1.0, v105
	s_waitcnt vmcnt(9)
	v_add_f32_e32 v16, 1.0, v106
	v_add_f32_e32 v17, 1.0, v107
	v_add_f32_e32 v18, 1.0, v108
	v_add_f32_e32 v19, 1.0, v109
	s_waitcnt vmcnt(6)
	v_fma_f32 v11, v11, v12, v120
	v_fma_f32 v12, v27, v13, v121
	v_fma_f32 v13, v28, v14, v122
	v_fma_f32 v41, v33, v15, v123
	s_waitcnt vmcnt(5)
	v_fma_f32 v14, v32, v16, v124
	v_fma_f32 v15, v31, v17, v125
	v_fma_f32 v16, v30, v18, v126
	v_fma_f32 v45, v7, v19, v127
	v_cvt_pk_bf16_f32 v12, v11, v12
	v_cvt_pk_bf16_f32 v13, v13, v41
	v_cvt_pk_bf16_f32 v14, v14, v15
	v_cvt_pk_bf16_f32 v15, v16, v45
	global_store_dwordx4 v[56:57], v[12:15], off offset:1024
	s_branch .LBB0_585

; __device__ __forceinline__ float bflo(unsigned w) { return __uint_as_float(w << 16); }
; __device__ __forceinline__ float bfhi(unsigned w) { return __uint_as_float(w & 0xffff0000u); }
; __device__ __forceinline__ float wave_sum(float v) {
; #pragma unroll
;     for (int o = 32; o > 0; o >>= 1) v += __shfl_xor(v, o);
;     return v;
; }
; __device__ __forceinline__ void norm_rows_b(const bf16_t* hb, int r_begin, int nrows, int stride, int second_off, const float* modl, int shoff, int scoff, bf16_t* xl) {
;     ...
;     for (int r = r_begin; r < nrows; r += stride) {
;         const int r1 = r + second_off; const bool two = r1 < nrows;
;         u32x4 w[2][2]; float s[2];
; #pragma unroll
;         for (int q = 0; q < 2; ++q) { const bf16_t* xr = hb + (size_t)(q ? (two ? r1 : r) : r) * DM + 8 * lane; w[q][0] = *(const u32x4*)(xr); w[q][1] = *(const u32x4*)(xr + 512); }
;         float v[2][16];
; #pragma unroll
;         for (int q = 0; q < 2; ++q) { float a = 0.f;
; #pragma unroll
;             for (int h = 0; h < 2; ++h)
; #pragma unroll
;                 for (int e = 0; e < 4; ++e) { const float lo = bflo(w[q][h][e]), hi = bfhi(w[q][h][e]); v[q][8 * h + 2 * e] = lo; v[q][8 * h + 2 * e + 1] = hi; a += lo * lo + hi * hi; }
;             s[q] = a; }
; #pragma unroll
;         for (int o = 32; o > 0; o >>= 1) { s[0] += __shfl_xor(s[0], o); s[1] += __shfl_xor(s[1], o); }
; #pragma unroll
;         for (int q = 0; q < 2; ++q) { if (q == 1 && !two) break; const int rr = q ? r1 : r; const int cond = rr < MLAT ? (rr >> 13) : 8; const float* mp = modl + cond * 6144;
;             const float rstd = rsqrtf(s[q] * (1.0f / DM) + EPS);
.LBB0_984:
	v_ashrrev_i32_e32 v13, 31, v12
	v_lshlrev_b64 v[50:51], 11, v[12:13]
	s_waitcnt lgkmcnt(0)
	v_lshl_add_u64 v[10:11], v[2:3], 0, v[50:51]
	global_load_dwordx4 v[18:21], v[10:11], off
	global_load_dwordx4 v[22:25], v[10:11], off offset:1024
	v_add_u32_e32 v10, s34, v12
	v_ashrrev_i32_e32 v7, 13, v12
	v_cmp_gt_i32_e32 vcc, s22, v10
	v_mul_i32_i24_e32 v14, 0x1800, v7
	v_ashrrev_i32_e32 v15, 31, v14
	v_cndmask_b32_e32 v12, v12, v10, vcc
	v_ashrrev_i32_e32 v13, 31, v12
	v_lshl_add_u64 v[14:15], v[14:15], 2, s[16:17]
	v_lshlrev_b64 v[12:13], 11, v[12:13]
	v_lshl_add_u64 v[52:53], v[14:15], 0, s[18:19]
	v_lshl_add_u64 v[12:13], v[2:3], 0, v[12:13]
	v_lshl_add_u64 v[34:35], v[52:53], 0, v[0:1]
	global_load_dwordx4 v[30:33], v[12:13], off
	global_load_dwordx4 v[80:83], v[34:35], off offset:2064
	global_load_dwordx4 v[84:87], v[34:35], off offset:2048
	global_load_dwordx4 v[26:29], v[34:35], off
	s_nop 0
	global_load_dwordx4 v[34:37], v[34:35], off offset:16
	v_lshl_add_u64 v[54:55], v[14:15], 0, s[20:21]
	global_load_dwordx4 v[38:41], v[12:13], off offset:1024
	v_lshl_add_u64 v[12:13], v[54:55], 0, v[0:1]
	global_load_dwordx4 v[88:91], v[12:13], off offset:2064
	global_load_dwordx4 v[92:95], v[12:13], off offset:2048
	global_load_dwordx4 v[42:45], v[12:13], off offset:16
	global_load_dwordx4 v[46:49], v[12:13], off
	v_lshl_add_u64 v[60:61], v[4:5], 0, v[50:51]
	v_lshl_add_u64 v[50:51], v[54:55], 0, v[8:9]
	v_ashrrev_i32_e32 v148, 13, v10
	v_mul_i32_i24_e32 v148, 0x1800, v148
	v_ashrrev_i32_e32 v149, 31, v148
	v_lshl_add_u64 v[96:97], v[148:149], 2, s[16:17]
	v_lshl_add_u64 v[98:99], v[96:97], 0, s[18:19]
	v_lshl_add_u64 v[100:101], v[98:99], 0, v[0:1]
	v_lshl_add_u64 v[102:103], v[96:97], 0, s[20:21]
	global_load_dwordx4 v[104:107], v[100:101], off offset:2048
	global_load_dwordx4 v[108:111], v[100:101], off offset:2064
	global_load_dwordx4 v[112:115], v[100:101], off
	global_load_dwordx4 v[116:119], v[100:101], off offset:16
	v_lshl_add_u64 v[120:121], v[102:103], 0, v[0:1]
	global_load_dwordx4 v[122:125], v[120:121], off offset:2048
	global_load_dwordx4 v[126:129], v[120:121], off offset:2064
	global_load_dwordx4 v[130:133], v[120:121], off
	global_load_dwordx4 v[134:137], v[120:121], off offset:16
	s_waitcnt vmcnt(19)
	v_and_b32_e32 v11, 0xffff0000, v18
	v_and_b32_e32 v63, 0xffff0000, v19
	v_lshlrev_b32_e32 v7, 16, v18
	v_lshlrev_b32_e32 v62, 16, v19
	v_and_b32_e32 v65, 0xffff0000, v20
	s_waitcnt vmcnt(18)
	v_lshlrev_b32_e32 v56, 16, v22
	v_and_b32_e32 v58, 0xffff0000, v22
	v_mul_f32_e32 v17, v11, v11
	v_mul_f32_e32 v22, v63, v63
	v_lshlrev_b32_e32 v64, 16, v20
	v_and_b32_e32 v67, 0xffff0000, v21
	v_lshlrev_b32_e32 v57, 16, v23
	v_and_b32_e32 v59, 0xffff0000, v23
	v_mul_f32_e32 v23, v65, v65
	v_fmac_f32_e32 v17, v7, v7
	v_fmac_f32_e32 v22, v62, v62
	v_lshlrev_b32_e32 v66, 16, v21
	v_lshlrev_b32_e32 v14, 16, v24
	v_and_b32_e32 v12, 0xffff0000, v24
	v_mul_f32_e32 v24, v67, v67
	v_fmac_f32_e32 v23, v64, v64
	v_add_f32_e32 v17, v17, v22
	v_pk_mul_f32 v[18:19], v[58:59], v[58:59]
	v_fmac_f32_e32 v24, v66, v66
	v_add_f32_e32 v17, v23, v17
	v_and_b32_e32 v13, 0xffff0000, v25
	v_pk_fma_f32 v[18:19], v[56:57], v[56:57], v[18:19]
	v_add_f32_e32 v17, v24, v17
	v_lshlrev_b32_e32 v15, 16, v25
	v_pk_mul_f32 v[20:21], v[12:13], v[12:13]
	v_add_f32_e32 v17, v18, v17
	v_pk_fma_f32 v[20:21], v[14:15], v[14:15], v[20:21]
	v_add_f32_e32 v17, v19, v17
	v_add_f32_e32 v17, v20, v17
	v_add_f32_e32 v17, v21, v17
	s_waitcnt vmcnt(14)
	v_add_f32_e32 v25, 1.0, v29
	v_add_f32_e32 v20, 1.0, v26
	v_add_f32_e32 v21, 1.0, v27
	v_add_f32_e32 v24, 1.0, v28
	s_waitcnt lgkmcnt(0)
	s_nop 1
	v_add_f32_dpp v17, v17, v17 quad_perm:[1,0,3,2] row_mask:0xf bank_mask:0xf
	s_waitcnt vmcnt(13)
	v_add_f32_e32 v26, 1.0, v34
	v_add_f32_e32 v27, 1.0, v36
	v_add_f32_e32 v28, 1.0, v37
	v_lshl_add_u64 v[22:23], v[52:53], 0, v[8:9]
	s_waitcnt lgkmcnt(0)
	s_nop 1
	v_add_f32_dpp v17, v17, v17 quad_perm:[2,3,0,1] row_mask:0xf bank_mask:0xf
	s_waitcnt lgkmcnt(0)
	s_nop 1
	v_add_f32_dpp v17, v17, v17 row_half_mirror row_mask:0xf bank_mask:0xf
	s_waitcnt lgkmcnt(0)
	s_nop 1
	v_add_f32_dpp v18, v17, v17 row_mirror row_mask:0xf bank_mask:0xf
	v_lshlrev_b32_e32 v17, 16, v30
	s_waitcnt lgkmcnt(0)
	s_nop 1
	v_add_f32_dpp v18, v18, v18 row_bcast:15 row_mask:0xa bank_mask:0xf
	s_waitcnt lgkmcnt(0)
	s_nop 1
	v_add_f32_dpp v18, v18, v18 row_bcast:31 row_mask:0xc bank_mask:0xf
	s_nop 0
	v_readlane_b32 s100, v18, 63
	s_nop 1
	v_mov_b32_e32 v18, s100
	v_fmamk_f32 v18, v18, 0x3a800000, v16
	v_mul_f32_e32 v19, 0x4b800000, v18
	v_cmp_gt_f32_e64 s[2:3], s23, v18
	s_nop 1
	v_cndmask_b32_e64 v18, v18, v19, s[2:3]
	v_rsq_f32_e32 v18, v18
	v_add_f32_e32 v19, 1.0, v35
	v_mul_f32_e32 v29, 0x45800000, v18
	v_cndmask_b32_e64 v54, v18, v29, s[2:3]
	v_mul_f32_e32 v7, v54, v7
	v_mul_f32_e32 v11, v54, v11
	v_mul_f32_e32 v18, v54, v62
	v_mul_f32_e32 v34, v54, v64
	v_mul_f32_e32 v29, v54, v63
	v_mul_f32_e32 v35, v54, v65
	v_mul_f32_e32 v36, v54, v66
	v_mul_f32_e32 v37, v54, v67
	s_waitcnt vmcnt(8)
; __device__ __forceinline__ unsigned cvt_pk_bf16(float lo, float hi) { unsigned r; asm volatile("v_cvt_pk_bf16_f32 %0, %1, %2" : "=v"(r) : "v"(lo), "v"(hi)); return r; }
; __device__ __forceinline__ float bflo(unsigned w) { return __uint_as_float(w << 16); }
; __device__ __forceinline__ float bfhi(unsigned w) { return __uint_as_float(w & 0xffff0000u); }
; __device__ __forceinline__ float wave_sum(float v) {
; #pragma unroll
;     for (int o = 32; o > 0; o >>= 1) v += __shfl_xor(v, o);
;     return v;
; }
; __device__ __forceinline__ void norm_rows_b(const bf16_t* hb, int r_begin, int nrows, int stride, int second_off, const float* modl, int shoff, int scoff, bf16_t* xl) {
;     ...
;         for (int q = 0; q < 2; ++q) { float a = 0.f;
; #pragma unroll
;             for (int h = 0; h < 2; ++h)
; #pragma unroll
;                 for (int e = 0; e < 4; ++e) { const float lo = bflo(w[q][h][e]), hi = bfhi(w[q][h][e]); v[q][8 * h + 2 * e] = lo; v[q][8 * h + 2 * e + 1] = hi; a += lo * lo + hi * hi; }
;             s[q] = a; }
; #pragma unroll
;         for (int o = 32; o > 0; o >>= 1) { s[0] += __shfl_xor(s[0], o); s[1] += __shfl_xor(s[1], o); }
; #pragma unroll
;         for (int q = 0; q < 2; ++q) { if (q == 1 && !two) break; const int rr = q ? r1 : r; const int cond = rr < MLAT ? (rr >> 13) : 8; const float* mp = modl + cond * 6144;
;             const float rstd = rsqrtf(s[q] * (1.0f / DM) + EPS);
; #pragma unroll
;             for (int h = 0; h < 2; ++h) { const int col = 8 * lane + 512 * h; const f32x4 sc0 = *(const f32x4*)(mp + scoff + col), sc1 = *(const f32x4*)(mp + scoff + col + 4), sh0 = *(const f32x4*)(mp + shoff + col), sh1 = *(const f32x4*)(mp + shoff + col + 4);
;                 u32x4 o;
;                 o.x = cvt_pk_bf16(v[q][8 * h + 0] * rstd * (sc0[0] + 1.0f) + sh0[0], v[q][8 * h + 1] * rstd * (sc0[1] + 1.0f) + sh0[1]);
;                 o.y = cvt_pk_bf16(v[q][8 * h + 2] * rstd * (sc0[2] + 1.0f) + sh0[2], v[q][8 * h + 3] * rstd * (sc0[3] + 1.0f) + sh0[3]);
;                 o.z = cvt_pk_bf16(v[q][8 * h + 4] * rstd * (sc1[0] + 1.0f) + sh1[0], v[q][8 * h + 5] * rstd * (sc1[1] + 1.0f) + sh1[1]);
;                 o.w = cvt_pk_bf16(v[q][8 * h + 6] * rstd * (sc1[2] + 1.0f) + sh1[2], v[q][8 * h + 7] * rstd * (sc1[3] + 1.0f) + sh1[3]);
;                 *(u32x4*)(xl + (size_t)rr * DM + col) = o; } }
	v_fma_f32 v7, v20, v7, v46
	v_fma_f32 v11, v21, v11, v47
	v_fma_f32 v20, v24, v18, v48
	v_fma_f32 v21, v26, v34, v42
	v_fmac_f32_e32 v49, v25, v29
	v_fma_f32 v24, v19, v35, v43
	v_fma_f32 v25, v27, v36, v44
	v_fmac_f32_e32 v45, v28, v37
	v_cvt_pk_bf16_f32 v18, v7, v11
	v_cvt_pk_bf16_f32 v19, v20, v49
	v_cvt_pk_bf16_f32 v20, v21, v24
	v_cvt_pk_bf16_f32 v21, v25, v45
	global_store_dwordx4 v[60:61], v[18:21], off
	s_nop 0
	v_and_b32_e32 v24, 0xffff0000, v30
	v_and_b32_e32 v28, 0xffff0000, v31
	v_lshlrev_b32_e32 v27, 16, v31
	v_and_b32_e32 v30, 0xffff0000, v32
	v_mul_f32_e32 v7, v24, v24
	v_mul_f32_e32 v11, v28, v28
	v_lshlrev_b32_e32 v29, 16, v32
	v_lshlrev_b32_e32 v31, 16, v33
	v_and_b32_e32 v32, 0xffff0000, v33
	v_mul_f32_e32 v33, v30, v30
	v_fmac_f32_e32 v7, v17, v17
	v_fmac_f32_e32 v11, v27, v27
	v_lshlrev_b32_e32 v26, 16, v38
	v_and_b32_e32 v25, 0xffff0000, v38
	v_mul_f32_e32 v38, v32, v32
	v_fmac_f32_e32 v33, v29, v29
	v_add_f32_e32 v7, v7, v11
	v_lshlrev_b32_e32 v23, 16, v39
	v_and_b32_e32 v22, 0xffff0000, v39
	v_mul_f32_e32 v39, v25, v25
	v_fmac_f32_e32 v38, v31, v31
	v_add_f32_e32 v7, v33, v7
	v_lshlrev_b32_e32 v21, 16, v40
	v_and_b32_e32 v20, 0xffff0000, v40
	v_mul_f32_e32 v40, v22, v22
	v_fmac_f32_e32 v39, v26, v26
	v_add_f32_e32 v7, v38, v7
	v_lshlrev_b32_e32 v19, 16, v41
	v_and_b32_e32 v18, 0xffff0000, v41
	v_mul_f32_e32 v41, v20, v20
	v_fmac_f32_e32 v40, v23, v23
	v_add_f32_e32 v7, v39, v7
	v_mul_f32_e32 v55, v18, v18
	v_fmac_f32_e32 v41, v21, v21
	v_add_f32_e32 v7, v40, v7
	v_fmac_f32_e32 v55, v19, v19
	v_add_f32_e32 v7, v41, v7
	v_add_f32_e32 v7, v55, v7
	v_mul_f32_e32 v14, v54, v14
	v_mul_f32_e32 v15, v54, v15
	v_mul_f32_e32 v33, v54, v56
	v_mul_f32_e32 v38, v54, v58
	s_waitcnt lgkmcnt(0)
	s_nop 1
	v_add_f32_dpp v7, v7, v7 quad_perm:[1,0,3,2] row_mask:0xf bank_mask:0xf
	v_mul_f32_e32 v39, v54, v57
	v_mul_f32_e32 v40, v54, v59
	v_mul_f32_e32 v12, v54, v12
	v_mul_f32_e32 v13, v54, v13
	s_waitcnt lgkmcnt(0)
	s_nop 1
	v_add_f32_dpp v7, v7, v7 quad_perm:[2,3,0,1] row_mask:0xf bank_mask:0xf
	s_waitcnt lgkmcnt(0)
	s_nop 1
	v_add_f32_dpp v7, v7, v7 row_half_mirror row_mask:0xf bank_mask:0xf
	s_waitcnt lgkmcnt(0)
	s_nop 1
	v_add_f32_dpp v7, v7, v7 row_mirror row_mask:0xf bank_mask:0xf
	s_waitcnt lgkmcnt(0)
	s_nop 1
	v_add_f32_dpp v7, v7, v7 row_bcast:15 row_mask:0xa bank_mask:0xf
	s_waitcnt vmcnt(17)
	v_add_f32_e32 v34, 1.0, v80
	v_add_f32_e32 v36, 1.0, v82
	s_waitcnt vmcnt(16)
	v_add_f32_e32 v41, 1.0, v84
	v_add_f32_e32 v42, 1.0, v85
	v_add_f32_e32 v43, 1.0, v86
	v_add_f32_e32 v44, 1.0, v87
	v_add_f32_e32 v35, 1.0, v81
	v_add_f32_e32 v37, 1.0, v83
	s_waitcnt vmcnt(12)
	v_fma_f32 v14, v14, v34, v88
	v_fma_f32 v15, v15, v36, v90
	s_waitcnt vmcnt(11)
	v_fma_f32 v33, v41, v33, v92
	v_fma_f32 v38, v42, v38, v93
	v_fma_f32 v39, v43, v39, v94
	v_fma_f32 v53, v44, v40, v95
	v_fma_f32 v34, v12, v35, v89
	v_fma_f32 v49, v13, v37, v91
	v_cvt_pk_bf16_f32 v12, v33, v38
	v_cvt_pk_bf16_f32 v13, v39, v53
	v_cvt_pk_bf16_f32 v14, v14, v34
	v_cvt_pk_bf16_f32 v15, v15, v49
	global_store_dwordx4 v[60:61], v[12:15], off offset:1024
	s_and_saveexec_b64 s[2:3], vcc
	s_cbranch_execz .LBB0_983
	s_waitcnt lgkmcnt(0)
	v_mov_b32_e32 v33, v7
	s_nop 1
	v_add_f32_dpp v33, v33, v33 row_bcast:31 row_mask:0xc bank_mask:0xf
	s_nop 0
	v_readlane_b32 s101, v33, 63
	s_nop 1
	v_mov_b32_e32 v33, s101
	v_fmamk_f32 v33, v33, 0x3a800000, v16
	v_mul_f32_e32 v50, 0x4b800000, v33
	v_cmp_gt_f32_e32 vcc, s23, v33
	v_ashrrev_i32_e32 v11, 31, v10
	v_mov_b32_e32 v7, v1
	v_cndmask_b32_e32 v33, v33, v50, vcc
	v_rsq_f32_e32 v33, v33
	v_lshlrev_b64 v[50:51], 11, v[10:11]
	v_lshl_add_u64 v[50:51], v[4:5], 0, v[50:51]
	v_lshl_add_u64 v[46:47], v[98:99], 0, v[6:7]
	v_mul_f32_e32 v11, 0x45800000, v33
	v_cndmask_b32_e32 v11, v33, v11, vcc
	v_mul_f32_e32 v17, v11, v17
	v_mul_f32_e32 v24, v11, v24
	v_mul_f32_e32 v27, v11, v27
	v_mul_f32_e32 v28, v11, v28
	v_mul_f32_e32 v29, v11, v29
	v_mul_f32_e32 v30, v11, v30
	v_mul_f32_e32 v31, v11, v31
	v_mul_f32_e32 v32, v11, v32
	v_mul_f32_e32 v23, v11, v23
	v_mul_f32_e32 v22, v11, v22
	v_mul_f32_e32 v21, v11, v21
	v_mul_f32_e32 v20, v11, v20
	v_mul_f32_e32 v19, v11, v19
	s_waitcnt vmcnt(7)
	v_add_f32_e32 v12, 1.0, v112
	v_add_f32_e32 v13, 1.0, v113
	v_add_f32_e32 v14, 1.0, v114
	v_add_f32_e32 v15, 1.0, v115
	s_waitcnt vmcnt(6)
	v_add_f32_e32 v33, 1.0, v116
	v_add_f32_e32 v34, 1.0, v117
	v_add_f32_e32 v35, 1.0, v118
	v_add_f32_e32 v36, 1.0, v119
	s_waitcnt vmcnt(3)
	v_fma_f32 v12, v17, v12, v130
	v_fma_f32 v13, v24, v13, v131
	v_fma_f32 v14, v27, v14, v132
	v_fma_f32 v41, v28, v15, v133
	s_waitcnt vmcnt(2)
	v_fma_f32 v15, v29, v33, v134
	v_fma_f32 v17, v30, v34, v135
	v_fma_f32 v24, v31, v35, v136
	v_fma_f32 v45, v32, v36, v137
	v_cvt_pk_bf16_f32 v12, v12, v13
	v_cvt_pk_bf16_f32 v13, v14, v41
	v_cvt_pk_bf16_f32 v14, v15, v17
	v_cvt_pk_bf16_f32 v15, v24, v45
	global_store_dwordx4 v[50:51], v[12:15], off
	s_nop 0
	v_lshl_add_u64 v[36:37], v[102:103], 0, v[6:7]
	s_nop 0
	v_mul_f32_e32 v7, v11, v26
	v_mul_f32_e32 v17, v11, v25
	v_mul_f32_e32 v11, v11, v18
	s_waitcnt vmcnt(10)
	v_add_f32_e32 v12, 1.0, v104
	v_add_f32_e32 v13, 1.0, v105
	v_add_f32_e32 v14, 1.0, v106
	v_add_f32_e32 v15, 1.0, v107
	s_waitcnt vmcnt(9)
	v_add_f32_e32 v18, 1.0, v108
	v_add_f32_e32 v24, 1.0, v109
	v_add_f32_e32 v25, 1.0, v110
	v_add_f32_e32 v26, 1.0, v111
	s_waitcnt vmcnt(6)
	v_fma_f32 v7, v7, v12, v122
	v_fma_f32 v12, v17, v13, v123
	v_fma_f32 v13, v23, v14, v124
	v_fma_f32 v35, v22, v15, v125
	s_waitcnt vmcnt(5)
	v_fma_f32 v14, v21, v18, v126
	v_fma_f32 v15, v20, v24, v127
	v_fma_f32 v17, v19, v25, v128
	v_fma_f32 v39, v11, v26, v129
	v_cvt_pk_bf16_f32 v12, v7, v12
	v_cvt_pk_bf16_f32 v13, v13, v35
	v_cvt_pk_bf16_f32 v14, v14, v15
	v_cvt_pk_bf16_f32 v15, v17, v39
	global_store_dwordx4 v[50:51], v[12:15], off offset:1024
	s_branch .LBB0_983

; __device__ __forceinline__ int tid_fresh() { int t = (int)threadIdx.x; asm volatile("" : "+v"(t)); return t; }
; __device__ __forceinline__ float bflo(unsigned w) { return __uint_as_float(w << 16); }
; __device__ __forceinline__ float bfhi(unsigned w) { return __uint_as_float(w & 0xffff0000u); }
; __device__ __forceinline__ float wave_sum(float v) {
; #pragma unroll
;     for (int o = 32; o > 0; o >>= 1) v += __shfl_xor(v, o);
;     return v;
; }
; __device__ __forceinline__ void final_norm_phase(const bf16_t* hb, float* out, const float* g) {
;     const int lane = tid_fresh() & 63, gw = blockIdx.x * 8 + (tid_fresh() >> 6), NGW = gridDim.x * 8;
;     for (int r = gw; r < MLAT; r += NGW) {
;         const bf16_t* xr = hb + (size_t)r * DM + 8 * lane; const u32x4 w0 = *(const u32x4*)(xr), w1 = *(const u32x4*)(xr + 512);
;         float v[16]; float s = 0.f;
; #pragma unroll
;         for (int e = 0; e < 4; ++e) { v[2 * e] = bflo(w0[e]); v[2 * e + 1] = bfhi(w0[e]); v[8 + 2 * e] = bflo(w1[e]); v[8 + 2 * e + 1] = bfhi(w1[e]); }
; #pragma unroll
;         for (int e = 0; e < 16; ++e) s += v[e] * v[e];
;         const float rstd = rsqrtf(wave_sum(s) * (1.0f / DM) + EPS);
; #pragma unroll
;         for (int h = 0; h < 2; ++h) { const int col = 8 * lane + 512 * h; const f32x4 g0 = *(const f32x4*)(g + col), g1 = *(const f32x4*)(g + col + 4);
;             f32x4 o0, o1;
; #pragma unroll
;             for (int e = 0; e < 4; ++e) { o0[e] = v[8 * h + e] * rstd * g0[e]; o1[e] = v[8 * h + 4 + e] * rstd * g1[e]; }
;             *(f32x4*)(out + (size_t)r * DM + col) = o0; *(f32x4*)(out + (size_t)r * DM + col + 4) = o1; }
;     }
; }
.Lfn_body:
	v_add_u32_e32 v0, s20, v0
	v_lshlrev_b32_e32 v26, 16, v64
	v_and_b32_e32 v27, 0xffff0000, v64
	v_lshlrev_b32_e32 v8, 16, v65
	v_and_b32_e32 v9, 0xffff0000, v65
	v_pk_mul_f32 v[36:37], v[26:27], v[26:27]
	v_pk_mul_f32 v[38:39], v[8:9], v[8:9]
	v_add_f32_e32 v36, v36, v37
	v_lshlrev_b32_e32 v24, 16, v66
	v_and_b32_e32 v25, 0xffff0000, v66
	v_add_f32_e32 v36, v38, v36
	v_lshlrev_b32_e32 v32, 16, v68
	v_and_b32_e32 v33, 0xffff0000, v68
	v_lshlrev_b32_e32 v34, 16, v69
	v_and_b32_e32 v35, 0xffff0000, v69
	v_pk_mul_f32 v[12:13], v[24:25], v[24:25]
	v_add_f32_e32 v36, v39, v36
	v_lshlrev_b32_e32 v10, 16, v67
	v_and_b32_e32 v11, 0xffff0000, v67
	v_add_f32_e32 v12, v12, v36
	v_lshlrev_b32_e32 v28, 16, v70
	v_and_b32_e32 v29, 0xffff0000, v70
	v_lshlrev_b32_e32 v30, 16, v71
	v_and_b32_e32 v31, 0xffff0000, v71
	global_load_dwordx4 v[64:67], v[4:5], off offset:-1024 nt
	global_load_dwordx4 v[68:71], v[4:5], off nt
	v_lshl_add_u64 v[4:5], v[4:5], 0, s[0:1]
	v_pk_mul_f32 v[14:15], v[10:11], v[10:11]
	v_add_f32_e32 v12, v13, v12
	v_add_f32_e32 v12, v14, v12
	v_pk_mul_f32 v[44:45], v[32:33], v[32:33]
	v_add_f32_e32 v12, v15, v12
	v_add_f32_e32 v12, v44, v12
	v_pk_mul_f32 v[46:47], v[34:35], v[34:35]
	v_add_f32_e32 v12, v45, v12
	v_add_f32_e32 v12, v46, v12
	v_pk_mul_f32 v[40:41], v[28:29], v[28:29]
	v_add_f32_e32 v12, v47, v12
	v_add_f32_e32 v12, v40, v12
	v_pk_mul_f32 v[42:43], v[30:31], v[30:31]
	v_add_f32_e32 v12, v41, v12
	v_add_f32_e32 v12, v42, v12
	v_add_f32_e32 v12, v43, v12
	s_waitcnt lgkmcnt(0)
	s_nop 1
	v_add_f32_dpp v12, v12, v12 quad_perm:[1,0,3,2] row_mask:0xf bank_mask:0xf
	s_waitcnt lgkmcnt(0)
	s_nop 1
	v_add_f32_dpp v12, v12, v12 quad_perm:[2,3,0,1] row_mask:0xf bank_mask:0xf
	s_waitcnt lgkmcnt(0)
	s_nop 1
	v_add_f32_dpp v12, v12, v12 row_half_mirror row_mask:0xf bank_mask:0xf
	s_waitcnt lgkmcnt(0)
	s_nop 1
	v_add_f32_dpp v12, v12, v12 row_mirror row_mask:0xf bank_mask:0xf
	s_waitcnt lgkmcnt(0)
	s_nop 1
	v_add_f32_dpp v12, v12, v12 row_bcast:15 row_mask:0xa bank_mask:0xf
	s_waitcnt lgkmcnt(0)
	s_nop 1
	v_add_f32_dpp v12, v12, v12 row_bcast:31 row_mask:0xc bank_mask:0xf
	s_nop 0
	v_readlane_b32 s100, v12, 63
	s_nop 1
	v_mov_b32_e32 v12, s100
	v_fmamk_f32 v12, v12, 0x3a800000, v1
	v_mul_f32_e32 v13, 0x4b800000, v12
	v_cmp_gt_f32_e32 vcc, s6, v12
	s_nop 1
	v_cndmask_b32_e32 v12, v12, v13, vcc
	v_rsq_f32_e32 v12, v12
	s_nop 0
	v_mul_f32_e32 v13, 0x45800000, v12
	v_cndmask_b32_e32 v36, v12, v13, vcc
	v_pk_mul_f32 v[12:13], v[36:37], v[26:27] op_sel_hi:[0,1]
	v_pk_mul_f32 v[8:9], v[36:37], v[8:9] op_sel_hi:[0,1]
	v_pk_mul_f32 v[24:25], v[36:37], v[24:25] op_sel_hi:[0,1]
	v_pk_mul_f32 v[14:15], v[36:37], v[10:11] op_sel_hi:[0,1]
	v_pk_mul_f32 v[10:11], v[50:51], v[8:9]
	v_pk_mul_f32 v[8:9], v[48:49], v[12:13]
	v_pk_mul_f32 v[14:15], v[54:55], v[14:15]
	v_pk_mul_f32 v[12:13], v[52:53], v[24:25]
	global_store_dwordx4 v[6:7], v[8:11], off
	global_store_dwordx4 v[6:7], v[12:15], off offset:16
	s_nop 0
	v_pk_mul_f32 v[16:17], v[36:37], v[34:35] op_sel_hi:[0,1]
	v_pk_mul_f32 v[18:19], v[36:37], v[32:33] op_sel_hi:[0,1]
	v_cmp_lt_i32_e32 vcc, s7, v0
	v_pk_mul_f32 v[20:21], v[36:37], v[30:31] op_sel_hi:[0,1]
	v_pk_mul_f32 v[22:23], v[36:37], v[28:29] op_sel_hi:[0,1]
	s_or_b64 s[4:5], vcc, s[4:5]
	v_pk_mul_f32 v[8:9], v[56:57], v[18:19]
	v_pk_mul_f32 v[10:11], v[58:59], v[16:17]
	v_pk_mul_f32 v[12:13], v[60:61], v[22:23]
	v_pk_mul_f32 v[14:15], v[62:63], v[20:21]
	global_store_dwordx4 v[6:7], v[8:11], off offset:2048
	global_store_dwordx4 v[6:7], v[12:15], off offset:2064
	v_lshl_add_u64 v[6:7], v[6:7], 0, s[2:3]
	s_andn2_b64 exec, exec, s[4:5]
	s_cbranch_execnz .LBB0_1231
